# phase-0 modulation GEMV: W rows prefetched two iterations ahead (two 4-quad sets + staging copy, loop unrolled x2)
# baseline (speedup 1.0000x reference)
.LBB0_861:
	s_mul_hi_i32 s0, s21, 0x2aaaaaab
	v_mov_b32_e32 v0, s19
	s_lshr_b32 s1, s0, 31
	ds_read2_b32 v[0:1], v0 offset1:1
	s_ashr_i32 s24, s0, 4
	s_add_i32 s24, s24, s1
	s_mul_i32 s0, s24, 0x60
	s_sub_i32 s2, s21, s0
	s_lshl_b32 s2, s2, 6
	s_waitcnt lgkmcnt(0)
	v_readfirstlane_b32 s0, v0
	v_readfirstlane_b32 s1, v1
	s_ashr_i32 s3, s2, 31
	s_mul_i32 s5, s24, 0x1800000
	v_lshl_add_u64 v[0:1], s[0:1], 0, v[38:39]
	s_lshl_b64 s[0:1], s[2:3], 2
	s_mul_hi_i32 s4, s24, 0x1800000
	s_add_u32 s0, s5, s0
	s_addc_u32 s1, s4, s1
	v_lshl_add_u64 v[40:41], v[0:1], 0, s[0:1]
	global_load_dwordx4 v[200:203], v[40:41], off
	s_mov_b64 s[0:1], 0x6000
	v_lshl_add_u64 v[248:249], v[40:41], 0, s[0:1]
	global_load_dwordx4 v[204:207], v[248:249], off
	s_mov_b64 s[0:1], 0xc000
	v_lshl_add_u64 v[248:249], v[40:41], 0, s[0:1]
	global_load_dwordx4 v[208:211], v[248:249], off
	s_mov_b64 s[0:1], 0x12000
	v_lshl_add_u64 v[248:249], v[40:41], 0, s[0:1]
	global_load_dwordx4 v[212:215], v[248:249], off
	s_mov_b64 s[0:1], 0x18000
	v_lshl_add_u64 v[248:249], v[40:41], 0, s[0:1]
	global_load_dwordx4 v[216:219], v[248:249], off
	s_mov_b64 s[0:1], 0x1e000
	v_lshl_add_u64 v[248:249], v[40:41], 0, s[0:1]
	global_load_dwordx4 v[220:223], v[248:249], off
	s_mov_b64 s[0:1], 0x24000
	v_lshl_add_u64 v[248:249], v[40:41], 0, s[0:1]
	global_load_dwordx4 v[224:227], v[248:249], off
	s_mov_b64 s[0:1], 0x2a000
	v_lshl_add_u64 v[248:249], v[40:41], 0, s[0:1]
	global_load_dwordx4 v[228:231], v[248:249], off
	v_mov_b32_e32 v0, 0
	s_mov_b64 s[4:5], 0
	v_mov_b32_e32 v66, v63
	v_mov_b32_e32 v1, v0
	v_mov_b32_e32 v2, v0
	v_mov_b32_e32 v3, v0
	v_mov_b32_e32 v4, v0
	v_mov_b32_e32 v5, v0
	v_mov_b32_e32 v6, v0
	v_mov_b32_e32 v7, v0
	v_mov_b32_e32 v8, v0
	v_mov_b32_e32 v9, v0
	v_mov_b32_e32 v10, v0
	v_mov_b32_e32 v11, v0
	v_mov_b32_e32 v12, v0
	v_mov_b32_e32 v13, v0
	v_mov_b32_e32 v14, v0
	v_mov_b32_e32 v15, v0
	v_mov_b32_e32 v16, v0
	v_mov_b32_e32 v17, v0
	v_mov_b32_e32 v18, v0
	v_mov_b32_e32 v19, v0
	v_mov_b32_e32 v20, v0
	v_mov_b32_e32 v21, v0
	v_mov_b32_e32 v22, v0
	v_mov_b32_e32 v23, v0
	v_mov_b32_e32 v24, v0
	v_mov_b32_e32 v25, v0
	v_mov_b32_e32 v26, v0
	v_mov_b32_e32 v27, v0
	v_mov_b32_e32 v28, v0
	v_mov_b32_e32 v29, v0
	v_mov_b32_e32 v30, v0
	v_mov_b32_e32 v31, v0
	v_mov_b32_e32 v32, v0
	v_mov_b32_e32 v33, v0
	v_mov_b32_e32 v34, v0
	v_mov_b32_e32 v35, v0
.LBB0_862:
	v_lshl_add_u64 v[54:55], v[40:41], 0, s[4:5]
	ds_read2_b32 v[56:57], v66 offset1:1
	ds_read2_b32 v[42:43], v66 offset0:2 offset1:3
	v_add_u32_e32 v44, 0x1000, v66
	v_add_u32_e32 v45, 0x2000, v66
	v_add_u32_e32 v46, 0x3000, v66
	v_add_u32_e32 v47, 0x4000, v66
	v_add_u32_e32 v48, 0x5000, v66
	v_add_u32_e32 v49, 0x6000, v66
	v_add_u32_e32 v67, 0x7000, v66
	v_add_u32_e32 v74, 0x8000, v66
	ds_read2_b32 v[58:59], v44 offset1:1
	ds_read2_b32 v[60:61], v45 offset1:1
	ds_read2_b32 v[68:69], v46 offset1:1
	ds_read2_b32 v[70:71], v47 offset1:1
	ds_read2_b32 v[72:73], v48 offset1:1
	ds_read2_b32 v[48:49], v49 offset1:1
	ds_read2_b32 v[46:47], v67 offset1:1
	ds_read2_b32 v[44:45], v74 offset1:1
	v_add_u32_e32 v67, 0x1008, v66
	s_add_u32 s4, s4, 0x18000
	s_addc_u32 s5, s5, 0
	s_cmp_lg_u32 s4, 0xc0000
	s_waitcnt vmcnt(4)
	v_mov_b32_e32 v232, v200
	v_mov_b32_e32 v233, v201
	v_mov_b32_e32 v234, v202
	v_mov_b32_e32 v235, v203
	v_mov_b32_e32 v236, v204
	v_mov_b32_e32 v237, v205
	v_mov_b32_e32 v238, v206
	v_mov_b32_e32 v239, v207
	v_mov_b32_e32 v240, v208
	v_mov_b32_e32 v241, v209
	v_mov_b32_e32 v242, v210
	v_mov_b32_e32 v243, v211
	v_mov_b32_e32 v244, v212
	v_mov_b32_e32 v245, v213
	v_mov_b32_e32 v246, v214
	v_mov_b32_e32 v247, v215
	s_cmp_lt_u32 s4, 0xa8000
	s_cbranch_scc0 .Lp0_nopf_a
	s_add_u32 s0, s4, 0x18000
	s_addc_u32 s1, s5, 0
	v_lshl_add_u64 v[248:249], v[40:41], 0, s[0:1]
	global_load_dwordx4 v[200:203], v[248:249], off
	s_mov_b64 s[0:1], 0x6000
	v_lshl_add_u64 v[248:249], v[248:249], 0, s[0:1]
	global_load_dwordx4 v[204:207], v[248:249], off
	s_mov_b64 s[0:1], 0x6000
	v_lshl_add_u64 v[248:249], v[248:249], 0, s[0:1]
	global_load_dwordx4 v[208:211], v[248:249], off
	s_mov_b64 s[0:1], 0x6000
	v_lshl_add_u64 v[248:249], v[248:249], 0, s[0:1]
	global_load_dwordx4 v[212:215], v[248:249], off
.Lp0_nopf_a:
	s_waitcnt lgkmcnt(5)
	v_pk_fma_f32 v[82:83], v[232:233], v[68:69], v[20:21] op_sel_hi:[1, 0, 1]
	s_waitcnt lgkmcnt(0)
	v_pk_fma_f32 v[20:21], v[232:233], v[44:45], v[0:1] op_sel_hi:[1, 0, 1]
	v_add_co_u32_e64 v0, s[0:1], s13, v54
	v_pk_fma_f32 v[84:85], v[234:235], v[68:69], v[22:23] op_sel_hi:[1, 0, 1]
	s_nop 0
	v_addc_co_u32_e64 v1, s[0:1], 0, v55, s[0:1]
	s_mov_b32 s0, 0xc000
	v_pk_fma_f32 v[22:23], v[234:235], v[44:45], v[2:3] op_sel_hi:[1, 0, 1]
	v_add_co_u32_e64 v2, s[0:1], s0, v54
	v_pk_fma_f32 v[74:75], v[232:233], v[58:59], v[28:29] op_sel_hi:[1, 0, 1]
	v_pk_fma_f32 v[76:77], v[234:235], v[58:59], v[30:31] op_sel_hi:[1, 0, 1]
	v_pk_fma_f32 v[78:79], v[232:233], v[60:61], v[24:25] op_sel_hi:[1, 0, 1]
	v_pk_fma_f32 v[80:81], v[234:235], v[60:61], v[26:27] op_sel_hi:[1, 0, 1]
	v_pk_fma_f32 v[28:29], v[232:233], v[48:49], v[8:9] op_sel_hi:[1, 0, 1]
	v_pk_fma_f32 v[30:31], v[234:235], v[48:49], v[10:11] op_sel_hi:[1, 0, 1]
	v_pk_fma_f32 v[24:25], v[232:233], v[46:47], v[4:5] op_sel_hi:[1, 0, 1]
	v_pk_fma_f32 v[26:27], v[234:235], v[46:47], v[6:7] op_sel_hi:[1, 0, 1]
	v_addc_co_u32_e64 v3, s[0:1], 0, v55, s[0:1]
	v_pk_fma_f32 v[32:33], v[232:233], v[56:57], v[32:33] op_sel_hi:[1, 0, 1]
	v_pk_fma_f32 v[86:87], v[232:233], v[70:71], v[16:17] op_sel_hi:[1, 0, 1]
	v_pk_fma_f32 v[90:91], v[232:233], v[72:73], v[12:13] op_sel_hi:[1, 0, 1]
	v_add_co_u32_e64 v50, s[0:1], s68, v54
	v_pk_fma_f32 v[34:35], v[234:235], v[56:57], v[34:35] op_sel_hi:[1, 0, 1]
	s_nop 0
	v_addc_co_u32_e64 v51, s[0:1], 0, v55, s[0:1]
	v_pk_fma_f32 v[88:89], v[234:235], v[70:71], v[18:19] op_sel_hi:[1, 0, 1]
	v_pk_fma_f32 v[92:93], v[234:235], v[72:73], v[14:15] op_sel_hi:[1, 0, 1]
	v_pk_fma_f32 v[12:13], v[236:237], v[56:57], v[32:33] op_sel:[0, 1, 0]
	v_pk_fma_f32 v[14:15], v[236:237], v[58:59], v[74:75] op_sel:[0, 1, 0]
	v_pk_fma_f32 v[18:19], v[238:239], v[58:59], v[76:77] op_sel:[0, 1, 0]
	v_pk_fma_f32 v[32:33], v[236:237], v[60:61], v[78:79] op_sel:[0, 1, 0]
	v_add_u32_e32 v74, 0x2008, v66
	v_add_u32_e32 v75, 0x3008, v66
	v_add_u32_e32 v76, 0x4008, v66
	v_add_u32_e32 v77, 0x5008, v66
	v_add_u32_e32 v78, 0x6008, v66
	v_pk_fma_f32 v[16:17], v[238:239], v[56:57], v[34:35] op_sel:[0, 1, 0]
	v_pk_fma_f32 v[34:35], v[238:239], v[60:61], v[80:81] op_sel:[0, 1, 0]
	v_pk_fma_f32 v[50:51], v[236:237], v[68:69], v[82:83] op_sel:[0, 1, 0]
	v_pk_fma_f32 v[52:53], v[238:239], v[68:69], v[84:85] op_sel:[0, 1, 0]
	v_pk_fma_f32 v[54:55], v[236:237], v[70:71], v[86:87] op_sel:[0, 1, 0]
	v_pk_fma_f32 v[56:57], v[238:239], v[70:71], v[88:89] op_sel:[0, 1, 0]
	v_add_u32_e32 v79, 0x7008, v66
	v_pk_fma_f32 v[58:59], v[236:237], v[72:73], v[90:91] op_sel:[0, 1, 0]
	v_pk_fma_f32 v[60:61], v[238:239], v[72:73], v[92:93] op_sel:[0, 1, 0]
	v_add_u32_e32 v80, 0x8008, v66
	ds_read2_b32 v[68:69], v67 offset1:1
	v_pk_fma_f32 v[28:29], v[236:237], v[48:49], v[28:29] op_sel:[0, 1, 0]
	v_pk_fma_f32 v[30:31], v[238:239], v[48:49], v[30:31] op_sel:[0, 1, 0]
	ds_read2_b32 v[48:49], v74 offset1:1
	ds_read2_b32 v[70:71], v75 offset1:1
	v_pk_fma_f32 v[24:25], v[236:237], v[46:47], v[24:25] op_sel:[0, 1, 0]
	v_pk_fma_f32 v[26:27], v[238:239], v[46:47], v[26:27] op_sel:[0, 1, 0]
	ds_read2_b32 v[46:47], v76 offset1:1
	ds_read2_b32 v[72:73], v77 offset1:1
	v_pk_fma_f32 v[8:9], v[236:237], v[44:45], v[20:21] op_sel:[0, 1, 0]
	v_pk_fma_f32 v[10:11], v[238:239], v[44:45], v[22:23] op_sel:[0, 1, 0]
	ds_read2_b32 v[44:45], v78 offset1:1
	ds_read2_b32 v[74:75], v79 offset1:1
	ds_read2_b32 v[76:77], v80 offset1:1
	v_pk_fma_f32 v[16:17], v[242:243], v[42:43], v[16:17] op_sel_hi:[1, 0, 1]
	v_pk_fma_f32 v[12:13], v[240:241], v[42:43], v[12:13] op_sel_hi:[1, 0, 1]
	s_waitcnt lgkmcnt(7)
	v_pk_fma_f32 v[18:19], v[242:243], v[68:69], v[18:19] op_sel_hi:[1, 0, 1]
	v_pk_fma_f32 v[14:15], v[240:241], v[68:69], v[14:15] op_sel_hi:[1, 0, 1]
	s_waitcnt lgkmcnt(6)
	v_pk_fma_f32 v[20:21], v[242:243], v[48:49], v[34:35] op_sel_hi:[1, 0, 1]
	v_pk_fma_f32 v[22:23], v[240:241], v[48:49], v[32:33] op_sel_hi:[1, 0, 1]
	s_waitcnt lgkmcnt(5)
	v_pk_fma_f32 v[52:53], v[242:243], v[70:71], v[52:53] op_sel_hi:[1, 0, 1]
	v_pk_fma_f32 v[50:51], v[240:241], v[70:71], v[50:51] op_sel_hi:[1, 0, 1]
	s_waitcnt lgkmcnt(4)
	v_pk_fma_f32 v[56:57], v[242:243], v[46:47], v[56:57] op_sel_hi:[1, 0, 1]
	v_pk_fma_f32 v[54:55], v[240:241], v[46:47], v[54:55] op_sel_hi:[1, 0, 1]
	s_waitcnt lgkmcnt(3)
	v_pk_fma_f32 v[60:61], v[242:243], v[72:73], v[60:61] op_sel_hi:[1, 0, 1]
	v_pk_fma_f32 v[58:59], v[240:241], v[72:73], v[58:59] op_sel_hi:[1, 0, 1]
	s_waitcnt lgkmcnt(2)
	v_pk_fma_f32 v[78:79], v[242:243], v[44:45], v[30:31] op_sel_hi:[1, 0, 1]
	v_pk_fma_f32 v[80:81], v[240:241], v[44:45], v[28:29] op_sel_hi:[1, 0, 1]
	s_waitcnt lgkmcnt(1)
	v_pk_fma_f32 v[82:83], v[242:243], v[74:75], v[26:27] op_sel_hi:[1, 0, 1]
	v_pk_fma_f32 v[84:85], v[240:241], v[74:75], v[24:25] op_sel_hi:[1, 0, 1]
	s_waitcnt lgkmcnt(0)
	v_pk_fma_f32 v[86:87], v[242:243], v[76:77], v[10:11] op_sel_hi:[1, 0, 1]
	v_pk_fma_f32 v[88:89], v[240:241], v[76:77], v[8:9] op_sel_hi:[1, 0, 1]
	v_add_u32_e32 v66, 16, v66
	v_pk_fma_f32 v[34:35], v[246:247], v[42:43], v[16:17] op_sel:[0, 1, 0]
	v_pk_fma_f32 v[32:33], v[244:245], v[42:43], v[12:13] op_sel:[0, 1, 0]
	v_pk_fma_f32 v[30:31], v[246:247], v[68:69], v[18:19] op_sel:[0, 1, 0]
	v_pk_fma_f32 v[28:29], v[244:245], v[68:69], v[14:15] op_sel:[0, 1, 0]
	v_pk_fma_f32 v[26:27], v[246:247], v[48:49], v[20:21] op_sel:[0, 1, 0]
	v_pk_fma_f32 v[24:25], v[244:245], v[48:49], v[22:23] op_sel:[0, 1, 0]
	v_pk_fma_f32 v[22:23], v[246:247], v[70:71], v[52:53] op_sel:[0, 1, 0]
	v_pk_fma_f32 v[20:21], v[244:245], v[70:71], v[50:51] op_sel:[0, 1, 0]
	v_pk_fma_f32 v[18:19], v[246:247], v[46:47], v[56:57] op_sel:[0, 1, 0]
	v_pk_fma_f32 v[16:17], v[244:245], v[46:47], v[54:55] op_sel:[0, 1, 0]
	v_pk_fma_f32 v[14:15], v[246:247], v[72:73], v[60:61] op_sel:[0, 1, 0]
	v_pk_fma_f32 v[12:13], v[244:245], v[72:73], v[58:59] op_sel:[0, 1, 0]
	v_pk_fma_f32 v[10:11], v[246:247], v[44:45], v[78:79] op_sel:[0, 1, 0]
	v_pk_fma_f32 v[8:9], v[244:245], v[44:45], v[80:81] op_sel:[0, 1, 0]
	v_pk_fma_f32 v[6:7], v[246:247], v[74:75], v[82:83] op_sel:[0, 1, 0]
	v_pk_fma_f32 v[4:5], v[244:245], v[74:75], v[84:85] op_sel:[0, 1, 0]
	v_pk_fma_f32 v[2:3], v[246:247], v[76:77], v[86:87] op_sel:[0, 1, 0]
	v_pk_fma_f32 v[0:1], v[244:245], v[76:77], v[88:89] op_sel:[0, 1, 0]
	v_lshl_add_u64 v[54:55], v[40:41], 0, s[4:5]
	ds_read2_b32 v[56:57], v66 offset1:1
	ds_read2_b32 v[42:43], v66 offset0:2 offset1:3
	v_add_u32_e32 v44, 0x1000, v66
	v_add_u32_e32 v45, 0x2000, v66
	v_add_u32_e32 v46, 0x3000, v66
	v_add_u32_e32 v47, 0x4000, v66
	v_add_u32_e32 v48, 0x5000, v66
	v_add_u32_e32 v49, 0x6000, v66
	v_add_u32_e32 v67, 0x7000, v66
	v_add_u32_e32 v74, 0x8000, v66
	ds_read2_b32 v[58:59], v44 offset1:1
	ds_read2_b32 v[60:61], v45 offset1:1
	ds_read2_b32 v[68:69], v46 offset1:1
	ds_read2_b32 v[70:71], v47 offset1:1
	ds_read2_b32 v[72:73], v48 offset1:1
	ds_read2_b32 v[48:49], v49 offset1:1
	ds_read2_b32 v[46:47], v67 offset1:1
	ds_read2_b32 v[44:45], v74 offset1:1
	v_add_u32_e32 v67, 0x1008, v66
	s_add_u32 s4, s4, 0x18000
	s_addc_u32 s5, s5, 0
	s_cmp_lg_u32 s4, 0xc0000
	s_cmp_eq_u32 s4, 0xc0000
	s_cbranch_scc1 .Lp0_w0_b
	s_waitcnt vmcnt(4)
	s_branch .Lp0_w1_b

.Lp0_w1_b:
	v_mov_b32_e32 v232, v216
	v_mov_b32_e32 v233, v217
	v_mov_b32_e32 v234, v218
	v_mov_b32_e32 v235, v219
	v_mov_b32_e32 v236, v220
	v_mov_b32_e32 v237, v221
	v_mov_b32_e32 v238, v222
	v_mov_b32_e32 v239, v223
	v_mov_b32_e32 v240, v224
	v_mov_b32_e32 v241, v225
	v_mov_b32_e32 v242, v226
	v_mov_b32_e32 v243, v227
	v_mov_b32_e32 v244, v228
	v_mov_b32_e32 v245, v229
	v_mov_b32_e32 v246, v230
	v_mov_b32_e32 v247, v231
	s_cmp_lt_u32 s4, 0xa8000
	s_cbranch_scc0 .Lp0_nopf_b
	s_add_u32 s0, s4, 0x18000
	s_addc_u32 s1, s5, 0
	v_lshl_add_u64 v[248:249], v[40:41], 0, s[0:1]
	global_load_dwordx4 v[216:219], v[248:249], off
	s_mov_b64 s[0:1], 0x6000
	v_lshl_add_u64 v[248:249], v[248:249], 0, s[0:1]
	global_load_dwordx4 v[220:223], v[248:249], off
	s_mov_b64 s[0:1], 0x6000
	v_lshl_add_u64 v[248:249], v[248:249], 0, s[0:1]
	global_load_dwordx4 v[224:227], v[248:249], off
	s_mov_b64 s[0:1], 0x6000
	v_lshl_add_u64 v[248:249], v[248:249], 0, s[0:1]
	global_load_dwordx4 v[228:231], v[248:249], off
.Lp0_nopf_b:
	s_waitcnt lgkmcnt(5)
	v_pk_fma_f32 v[82:83], v[232:233], v[68:69], v[20:21] op_sel_hi:[1, 0, 1]
	s_waitcnt lgkmcnt(0)
	v_pk_fma_f32 v[20:21], v[232:233], v[44:45], v[0:1] op_sel_hi:[1, 0, 1]
	v_add_co_u32_e64 v0, s[0:1], s13, v54
	v_pk_fma_f32 v[84:85], v[234:235], v[68:69], v[22:23] op_sel_hi:[1, 0, 1]
	s_nop 0
	v_addc_co_u32_e64 v1, s[0:1], 0, v55, s[0:1]
	s_mov_b32 s0, 0xc000
	v_pk_fma_f32 v[22:23], v[234:235], v[44:45], v[2:3] op_sel_hi:[1, 0, 1]
	v_add_co_u32_e64 v2, s[0:1], s0, v54
	v_pk_fma_f32 v[74:75], v[232:233], v[58:59], v[28:29] op_sel_hi:[1, 0, 1]
	v_pk_fma_f32 v[76:77], v[234:235], v[58:59], v[30:31] op_sel_hi:[1, 0, 1]
	v_pk_fma_f32 v[78:79], v[232:233], v[60:61], v[24:25] op_sel_hi:[1, 0, 1]
	v_pk_fma_f32 v[80:81], v[234:235], v[60:61], v[26:27] op_sel_hi:[1, 0, 1]
	v_pk_fma_f32 v[28:29], v[232:233], v[48:49], v[8:9] op_sel_hi:[1, 0, 1]
	v_pk_fma_f32 v[30:31], v[234:235], v[48:49], v[10:11] op_sel_hi:[1, 0, 1]
	v_pk_fma_f32 v[24:25], v[232:233], v[46:47], v[4:5] op_sel_hi:[1, 0, 1]
	v_pk_fma_f32 v[26:27], v[234:235], v[46:47], v[6:7] op_sel_hi:[1, 0, 1]
	v_addc_co_u32_e64 v3, s[0:1], 0, v55, s[0:1]
	v_pk_fma_f32 v[32:33], v[232:233], v[56:57], v[32:33] op_sel_hi:[1, 0, 1]
	v_pk_fma_f32 v[86:87], v[232:233], v[70:71], v[16:17] op_sel_hi:[1, 0, 1]
	v_pk_fma_f32 v[90:91], v[232:233], v[72:73], v[12:13] op_sel_hi:[1, 0, 1]
	v_add_co_u32_e64 v50, s[0:1], s68, v54
	v_pk_fma_f32 v[34:35], v[234:235], v[56:57], v[34:35] op_sel_hi:[1, 0, 1]
	s_nop 0
	v_addc_co_u32_e64 v51, s[0:1], 0, v55, s[0:1]
	v_pk_fma_f32 v[88:89], v[234:235], v[70:71], v[18:19] op_sel_hi:[1, 0, 1]
	v_pk_fma_f32 v[92:93], v[234:235], v[72:73], v[14:15] op_sel_hi:[1, 0, 1]
	v_pk_fma_f32 v[12:13], v[236:237], v[56:57], v[32:33] op_sel:[0, 1, 0]
	v_pk_fma_f32 v[14:15], v[236:237], v[58:59], v[74:75] op_sel:[0, 1, 0]
	v_pk_fma_f32 v[18:19], v[238:239], v[58:59], v[76:77] op_sel:[0, 1, 0]
	v_pk_fma_f32 v[32:33], v[236:237], v[60:61], v[78:79] op_sel:[0, 1, 0]
	v_add_u32_e32 v74, 0x2008, v66
	v_add_u32_e32 v75, 0x3008, v66
	v_add_u32_e32 v76, 0x4008, v66
	v_add_u32_e32 v77, 0x5008, v66
	v_add_u32_e32 v78, 0x6008, v66
	v_pk_fma_f32 v[16:17], v[238:239], v[56:57], v[34:35] op_sel:[0, 1, 0]
	v_pk_fma_f32 v[34:35], v[238:239], v[60:61], v[80:81] op_sel:[0, 1, 0]
	v_pk_fma_f32 v[50:51], v[236:237], v[68:69], v[82:83] op_sel:[0, 1, 0]
	v_pk_fma_f32 v[52:53], v[238:239], v[68:69], v[84:85] op_sel:[0, 1, 0]
	v_pk_fma_f32 v[54:55], v[236:237], v[70:71], v[86:87] op_sel:[0, 1, 0]
	v_pk_fma_f32 v[56:57], v[238:239], v[70:71], v[88:89] op_sel:[0, 1, 0]
	v_add_u32_e32 v79, 0x7008, v66
	v_pk_fma_f32 v[58:59], v[236:237], v[72:73], v[90:91] op_sel:[0, 1, 0]
	v_pk_fma_f32 v[60:61], v[238:239], v[72:73], v[92:93] op_sel:[0, 1, 0]
	v_add_u32_e32 v80, 0x8008, v66
	ds_read2_b32 v[68:69], v67 offset1:1
	v_pk_fma_f32 v[28:29], v[236:237], v[48:49], v[28:29] op_sel:[0, 1, 0]
	v_pk_fma_f32 v[30:31], v[238:239], v[48:49], v[30:31] op_sel:[0, 1, 0]
	ds_read2_b32 v[48:49], v74 offset1:1
	ds_read2_b32 v[70:71], v75 offset1:1
	v_pk_fma_f32 v[24:25], v[236:237], v[46:47], v[24:25] op_sel:[0, 1, 0]
	v_pk_fma_f32 v[26:27], v[238:239], v[46:47], v[26:27] op_sel:[0, 1, 0]
	ds_read2_b32 v[46:47], v76 offset1:1
	ds_read2_b32 v[72:73], v77 offset1:1
	v_pk_fma_f32 v[8:9], v[236:237], v[44:45], v[20:21] op_sel:[0, 1, 0]
	v_pk_fma_f32 v[10:11], v[238:239], v[44:45], v[22:23] op_sel:[0, 1, 0]
	ds_read2_b32 v[44:45], v78 offset1:1
	ds_read2_b32 v[74:75], v79 offset1:1
	ds_read2_b32 v[76:77], v80 offset1:1
	v_pk_fma_f32 v[16:17], v[242:243], v[42:43], v[16:17] op_sel_hi:[1, 0, 1]
	v_pk_fma_f32 v[12:13], v[240:241], v[42:43], v[12:13] op_sel_hi:[1, 0, 1]
	s_waitcnt lgkmcnt(7)
	v_pk_fma_f32 v[18:19], v[242:243], v[68:69], v[18:19] op_sel_hi:[1, 0, 1]
	v_pk_fma_f32 v[14:15], v[240:241], v[68:69], v[14:15] op_sel_hi:[1, 0, 1]
	s_waitcnt lgkmcnt(6)
	v_pk_fma_f32 v[20:21], v[242:243], v[48:49], v[34:35] op_sel_hi:[1, 0, 1]
	v_pk_fma_f32 v[22:23], v[240:241], v[48:49], v[32:33] op_sel_hi:[1, 0, 1]
	s_waitcnt lgkmcnt(5)
	v_pk_fma_f32 v[52:53], v[242:243], v[70:71], v[52:53] op_sel_hi:[1, 0, 1]
	v_pk_fma_f32 v[50:51], v[240:241], v[70:71], v[50:51] op_sel_hi:[1, 0, 1]
	s_waitcnt lgkmcnt(4)
	v_pk_fma_f32 v[56:57], v[242:243], v[46:47], v[56:57] op_sel_hi:[1, 0, 1]
	v_pk_fma_f32 v[54:55], v[240:241], v[46:47], v[54:55] op_sel_hi:[1, 0, 1]
	s_waitcnt lgkmcnt(3)
	v_pk_fma_f32 v[60:61], v[242:243], v[72:73], v[60:61] op_sel_hi:[1, 0, 1]
	v_pk_fma_f32 v[58:59], v[240:241], v[72:73], v[58:59] op_sel_hi:[1, 0, 1]
	s_waitcnt lgkmcnt(2)
	v_pk_fma_f32 v[78:79], v[242:243], v[44:45], v[30:31] op_sel_hi:[1, 0, 1]
	v_pk_fma_f32 v[80:81], v[240:241], v[44:45], v[28:29] op_sel_hi:[1, 0, 1]
	s_waitcnt lgkmcnt(1)
	v_pk_fma_f32 v[82:83], v[242:243], v[74:75], v[26:27] op_sel_hi:[1, 0, 1]
	v_pk_fma_f32 v[84:85], v[240:241], v[74:75], v[24:25] op_sel_hi:[1, 0, 1]
	s_waitcnt lgkmcnt(0)
	v_pk_fma_f32 v[86:87], v[242:243], v[76:77], v[10:11] op_sel_hi:[1, 0, 1]
	v_pk_fma_f32 v[88:89], v[240:241], v[76:77], v[8:9] op_sel_hi:[1, 0, 1]
	v_add_u32_e32 v66, 16, v66
	v_pk_fma_f32 v[34:35], v[246:247], v[42:43], v[16:17] op_sel:[0, 1, 0]
	v_pk_fma_f32 v[32:33], v[244:245], v[42:43], v[12:13] op_sel:[0, 1, 0]
	v_pk_fma_f32 v[30:31], v[246:247], v[68:69], v[18:19] op_sel:[0, 1, 0]
	v_pk_fma_f32 v[28:29], v[244:245], v[68:69], v[14:15] op_sel:[0, 1, 0]
	v_pk_fma_f32 v[26:27], v[246:247], v[48:49], v[20:21] op_sel:[0, 1, 0]
	v_pk_fma_f32 v[24:25], v[244:245], v[48:49], v[22:23] op_sel:[0, 1, 0]
	v_pk_fma_f32 v[22:23], v[246:247], v[70:71], v[52:53] op_sel:[0, 1, 0]
	v_pk_fma_f32 v[20:21], v[244:245], v[70:71], v[50:51] op_sel:[0, 1, 0]
	v_pk_fma_f32 v[18:19], v[246:247], v[46:47], v[56:57] op_sel:[0, 1, 0]
	v_pk_fma_f32 v[16:17], v[244:245], v[46:47], v[54:55] op_sel:[0, 1, 0]
	v_pk_fma_f32 v[14:15], v[246:247], v[72:73], v[60:61] op_sel:[0, 1, 0]
	v_pk_fma_f32 v[12:13], v[244:245], v[72:73], v[58:59] op_sel:[0, 1, 0]
	v_pk_fma_f32 v[10:11], v[246:247], v[44:45], v[78:79] op_sel:[0, 1, 0]
	v_pk_fma_f32 v[8:9], v[244:245], v[44:45], v[80:81] op_sel:[0, 1, 0]
	v_pk_fma_f32 v[6:7], v[246:247], v[74:75], v[82:83] op_sel:[0, 1, 0]
	v_pk_fma_f32 v[4:5], v[244:245], v[74:75], v[84:85] op_sel:[0, 1, 0]
	v_pk_fma_f32 v[2:3], v[246:247], v[76:77], v[86:87] op_sel:[0, 1, 0]
	v_pk_fma_f32 v[0:1], v[244:245], v[76:77], v[88:89] op_sel:[0, 1, 0]
	s_cmp_lg_u32 s4, 0xc0000
	s_cbranch_scc1 .LBB0_862
	ds_write_b128 v65, v[32:35] offset:36864
	ds_write_b128 v65, v[28:31] offset:37120
	ds_write_b128 v65, v[24:27] offset:37376
	ds_write_b128 v65, v[20:23] offset:37632
	ds_write_b128 v65, v[16:19] offset:37888
	ds_write_b128 v65, v[12:15] offset:38144
	ds_write_b128 v65, v[8:11] offset:38400
	ds_write_b128 v65, v[4:7] offset:38656
	ds_write_b128 v65, v[0:3] offset:38912
	s_waitcnt lgkmcnt(0)
	s_barrier
	s_and_saveexec_b64 s[4:5], vcc
	s_cbranch_execz .LBB0_860
	v_mov_b32_e32 v0, s20
	ds_read2_b32 v[0:1], v0 offset1:1
	s_mul_i32 s0, s24, 0x1800
	v_or_b32_e32 v4, s2, v62
	v_add_u32_e32 v2, s0, v4
	v_ashrrev_i32_e32 v5, 31, v4
	s_mul_i32 s24, s24, 9
	v_ashrrev_i32_e32 v3, 31, v2
	v_lshl_add_u64 v[4:5], v[4:5], 2, s[14:15]
	s_mov_b64 s[2:3], 0
	v_mov_b32_e32 v6, v36
